# winner emission: one position atomic per lane then store loop; weight-norm clamp 1e-6
# speedup vs baseline: 1.1007x; 1.0024x over previous
; template <int PASS> ...
;     ...
;         for (int e = 0; e < 8; ++e) { const unsigned char* tp = lp + (hb * 8 + e) * 2048; kf[e][0] = *(const h16x8*)(tp + ((fq ^ sw) << 4)); kf[e][1] = *(const h16x8*)(tp + (((fq + 4) ^ sw) << 4)); }
; #pragma unroll
;         for (int e = 0; e < 8; ++e) { const int T = Tbase + hb * 8 + e;
;             f32x4 a0 = (f32x4){0.f, 0.f, 0.f, 0.f}, a1 = a0;
;             a0 = __builtin_amdgcn_mfma_f32_16x16x32_f16(aq[0][0], kf[e][0], a0, 0, 0, 0); a0 = __builtin_amdgcn_mfma_f32_16x16x32_f16(aq[0][1], kf[e][1], a0, 0, 0, 0);
;             a1 = __builtin_amdgcn_mfma_f32_16x16x32_f16(aq[1][0], kf[e][0], a1, 0, 0, 0); a1 = __builtin_amdgcn_mfma_f32_16x16x32_f16(aq[1][1], kf[e][1], a1, 0, 0, 0);
;             const h16x2 z2 = (h16x2){(h16)0.f, (h16)0.f};
;             const h16x2 r0 = __builtin_elementwise_max(__builtin_bit_cast(h16x2, __builtin_amdgcn_cvt_pkrtz(a0[0], a0[1])), z2), r1 = __builtin_elementwise_max(__builtin_bit_cast(h16x2, __builtin_amdgcn_cvt_pkrtz(a0[2], a0[3])), z2);
;             const h16x2 r2 = __builtin_elementwise_max(__builtin_bit_cast(h16x2, __builtin_amdgcn_cvt_pkrtz(a1[0], a1[1])), z2), r3 = __builtin_elementwise_max(__builtin_bit_cast(h16x2, __builtin_amdgcn_cvt_pkrtz(a1[2], a1[3])), z2);
;             const float sa = __builtin_amdgcn_fdot2(r0, wp[0], __builtin_amdgcn_fdot2(r1, wp[1], __builtin_amdgcn_fdot2(r2, wp[2], __builtin_amdgcn_fdot2(r3, wp[3], 0.f, false), false), false), false);
;             const int key = 16 * T + fr;
;             if (key <= tq) {
;                 const unsigned bin = (unsigned)(int)fminf(fmaxf(sa * 32.f + 128.f, 0.f), 255.f);
;                 if (PASS == 1) { if (bin >= b0) atomicAdd(&myhist[fq * 256 + bin], 1u); }
; __device__ __forceinline__ void dsa_select(const h16* PROJ, unsigned short* IDX, int* CNT, unsigned char* shm, unsigned* bar, unsigned xcc, unsigned xrank) {
;     ...
;             float wv[8];
;             { const h16x8 w8 = *(const h16x8*)(PROJ + O_WI + (size_t)(tokbase + tq) * 8);
; #pragma unroll
;               for (int h = 0; h < 8; ++h) wv[h] = (float)w8[h] * 0.04419417382415922f; }
;             h16x2 wp[4];
; #pragma unroll
;             for (int h = 0; h < 4; ++h) { wp[h].x = (h16)wv[(h >> 1) * 4 + (h & 1) * 2]; wp[h].y = (h16)wv[(h >> 1) * 4 + (h & 1) * 2 + 1]; }
.LBB0_182:
	s_and_b32 s62, s4, 0x8000
	v_add_u32_e32 v64, s62, v134
	v_add_u32_e32 v122, v64, v135
	v_add_u32_e32 v123, v64, v136
	v_lshlrev_b32_e32 v121, 8, v121
	v_sub_u32_e32 v121, v115, v121
	v_sub_u32_e32 v78, v192, v121
	v_cmp_le_i32_e32 vcc, 0, v78
	s_cmp_eq_u64 vcc, -1
	s_cbranch_scc1 .Lp1_interior
	ds_read_b128 v[32:35], v122
	ds_read_b128 v[36:39], v123
	ds_read_b128 v[40:43], v122 offset:2048
	ds_read_b128 v[44:47], v123 offset:2048
	v_mov_b32_e32 v79, 0x437f0000
	v_mul_f32_e32 v88, v106, v106
	v_fmac_f32_e32 v88, v107, v107
	v_fmac_f32_e32 v88, v108, v108
	v_fmac_f32_e32 v88, v109, v109
	v_fmac_f32_e32 v88, v110, v110
	v_fmac_f32_e32 v88, v111, v111
	v_fmac_f32_e32 v88, v112, v112
	v_fmac_f32_e32 v88, v113, v113
	v_max_f32_e32 v88, 0x358637bd, v88
	v_rsq_f32_e32 v88, v88
	s_mov_b32 s62, 0x100001
	s_mov_b32 s63, 0x10000100
	v_mul_f32_e32 v88, 4.0, v88
	v_cvt_pkrtz_f16_f32 v88, v88, v88
	v_pk_mul_f16 v80, v193, v88
	v_pk_mul_f16 v81, v194, v88
	v_pk_mul_f16 v82, v195, v88
	v_pk_mul_f16 v83, v196, v88
	v_cndmask_b32_e64 v80, 0, v80, s[62:63]
	v_cndmask_b32_e64 v81, 0, v81, s[62:63]
	v_cndmask_b32_e64 v82, 0, v82, s[62:63]
	v_cndmask_b32_e64 v83, 0, v83, s[62:63]
	v_mov_b32_e32 v84, 0x43000000
	v_mov_b32_e32 v85, 0
	v_mov_b32_e32 v86, 0
	v_mov_b32_e32 v87, 0
	s_waitcnt lgkmcnt(2)
	v_mfma_f32_16x16x32_f16 v[48:51], v[0:3], v[32:35], 0
	v_mfma_f32_16x16x32_f16 v[52:55], v[8:11], v[32:35], 0
	v_mfma_f32_16x16x32_f16 v[48:51], v[4:7], v[36:39], v[48:51]
	v_mfma_f32_16x16x32_f16 v[52:55], v[12:15], v[36:39], v[52:55]
	s_nop 3
	ds_read_b128 v[32:35], v122 offset:4096
	ds_read_b128 v[36:39], v123 offset:4096
	s_waitcnt lgkmcnt(2)
	v_mfma_f32_16x16x32_f16 v[56:59], v[0:3], v[40:43], 0
	v_cvt_pkrtz_f16_f32 v67, v54, v55
	v_cvt_pkrtz_f16_f32 v66, v52, v53
	v_pk_max_f16 v67, v67, 0
	v_pk_max_f16 v66, v66, 0
	v_mfma_f32_16x16x32_f16 v[60:63], v[8:11], v[40:43], 0
	v_cvt_pkrtz_f16_f32 v65, v50, v51
	v_cvt_pkrtz_f16_f32 v64, v48, v49
	v_pk_max_f16 v65, v65, 0
	v_mfma_f32_16x16x32_f16 v[56:59], v[4:7], v[44:47], v[56:59]
	v_pk_max_f16 v64, v64, 0
	v_mfma_f32_16x16x32_f16 v[60:63], v[12:15], v[44:47], v[60:63]
	s_nop 3
	v_mfma_f32_16x16x32_f16 v[68:71], v[80:83], v[64:67], v[84:87]
	ds_read_b128 v[40:43], v122 offset:6144
	ds_read_b128 v[44:47], v123 offset:6144
	s_waitcnt lgkmcnt(2)
	v_mfma_f32_16x16x32_f16 v[48:51], v[0:3], v[32:35], 0
	v_cvt_pkrtz_f16_f32 v67, v62, v63
	v_cvt_pkrtz_f16_f32 v66, v60, v61
	v_pk_max_f16 v67, v67, 0
	v_pk_max_f16 v66, v66, 0
	v_mfma_f32_16x16x32_f16 v[52:55], v[8:11], v[32:35], 0
	v_cvt_pkrtz_f16_f32 v65, v58, v59
	v_cvt_pkrtz_f16_f32 v64, v56, v57
	v_med3_f32 v76, v68, 0, v79
	v_pk_max_f16 v65, v65, 0
	v_mfma_f32_16x16x32_f16 v[48:51], v[4:7], v[36:39], v[48:51]
	v_pk_max_f16 v64, v64, 0
	v_cvt_u32_f32_e32 v76, v76
	v_cmp_le_i32_e32 vcc, -240, v78
	v_mfma_f32_16x16x32_f16 v[52:55], v[12:15], v[36:39], v[52:55]
	v_lshl_add_u32 v77, v76, 2, v139
	s_and_b64 exec, exec, vcc
	ds_add_u32 v77, v212
	s_mov_b64 exec, -1
	v_mfma_f32_16x16x32_f16 v[72:75], v[80:83], v[64:67], v[84:87]
	ds_read_b128 v[32:35], v122 offset:8192
	ds_read_b128 v[36:39], v123 offset:8192
	s_waitcnt lgkmcnt(3)
	v_mfma_f32_16x16x32_f16 v[56:59], v[0:3], v[40:43], 0
	v_cvt_pkrtz_f16_f32 v67, v54, v55
	v_cvt_pkrtz_f16_f32 v66, v52, v53
	v_pk_max_f16 v67, v67, 0
	v_pk_max_f16 v66, v66, 0
	v_mfma_f32_16x16x32_f16 v[60:63], v[8:11], v[40:43], 0
	v_cvt_pkrtz_f16_f32 v65, v50, v51
	v_cvt_pkrtz_f16_f32 v64, v48, v49
	v_med3_f32 v76, v72, 0, v79
	v_pk_max_f16 v65, v65, 0
	v_mfma_f32_16x16x32_f16 v[56:59], v[4:7], v[44:47], v[56:59]
	v_pk_max_f16 v64, v64, 0
	v_cvt_u32_f32_e32 v76, v76
	v_cmp_le_i32_e32 vcc, -224, v78
	v_mfma_f32_16x16x32_f16 v[60:63], v[12:15], v[44:47], v[60:63]
	v_lshl_add_u32 v77, v76, 2, v139
	s_and_b64 exec, exec, vcc
	ds_add_u32 v77, v212
	s_mov_b64 exec, -1
	v_mfma_f32_16x16x32_f16 v[68:71], v[80:83], v[64:67], v[84:87]
	ds_read_b128 v[40:43], v122 offset:10240
	ds_read_b128 v[44:47], v123 offset:10240
	s_waitcnt lgkmcnt(3)
	v_mfma_f32_16x16x32_f16 v[48:51], v[0:3], v[32:35], 0
	v_cvt_pkrtz_f16_f32 v67, v62, v63
	v_cvt_pkrtz_f16_f32 v66, v60, v61
	v_pk_max_f16 v67, v67, 0
	v_pk_max_f16 v66, v66, 0
	v_mfma_f32_16x16x32_f16 v[52:55], v[8:11], v[32:35], 0
	v_cvt_pkrtz_f16_f32 v65, v58, v59
	v_cvt_pkrtz_f16_f32 v64, v56, v57
	v_med3_f32 v76, v68, 0, v79
	v_pk_max_f16 v65, v65, 0
	v_mfma_f32_16x16x32_f16 v[48:51], v[4:7], v[36:39], v[48:51]
	v_pk_max_f16 v64, v64, 0
	v_cvt_u32_f32_e32 v76, v76
	v_cmp_le_i32_e32 vcc, -208, v78
	v_mfma_f32_16x16x32_f16 v[52:55], v[12:15], v[36:39], v[52:55]
	v_lshl_add_u32 v77, v76, 2, v139
	s_and_b64 exec, exec, vcc
	ds_add_u32 v77, v212
	s_mov_b64 exec, -1
	v_mfma_f32_16x16x32_f16 v[72:75], v[80:83], v[64:67], v[84:87]
	ds_read_b128 v[32:35], v122 offset:12288
	ds_read_b128 v[36:39], v123 offset:12288
	s_waitcnt lgkmcnt(3)
	v_mfma_f32_16x16x32_f16 v[56:59], v[0:3], v[40:43], 0
	v_cvt_pkrtz_f16_f32 v67, v54, v55
	v_cvt_pkrtz_f16_f32 v66, v52, v53
	v_pk_max_f16 v67, v67, 0
	v_pk_max_f16 v66, v66, 0
	v_mfma_f32_16x16x32_f16 v[60:63], v[8:11], v[40:43], 0
	v_cvt_pkrtz_f16_f32 v65, v50, v51
	v_cvt_pkrtz_f16_f32 v64, v48, v49
	v_med3_f32 v76, v72, 0, v79
	v_pk_max_f16 v65, v65, 0
	v_mfma_f32_16x16x32_f16 v[56:59], v[4:7], v[44:47], v[56:59]
	v_pk_max_f16 v64, v64, 0
	v_cvt_u32_f32_e32 v76, v76
	v_cmp_le_i32_e32 vcc, -192, v78
	v_mfma_f32_16x16x32_f16 v[60:63], v[12:15], v[44:47], v[60:63]
	v_lshl_add_u32 v77, v76, 2, v139
	s_and_b64 exec, exec, vcc
	ds_add_u32 v77, v212
	s_mov_b64 exec, -1
	v_mfma_f32_16x16x32_f16 v[68:71], v[80:83], v[64:67], v[84:87]
	ds_read_b128 v[40:43], v122 offset:14336
	ds_read_b128 v[44:47], v123 offset:14336
	s_waitcnt lgkmcnt(3)
; template <int PASS> ...
;     ...
;         for (int e = 0; e < 8; ++e) { const unsigned char* tp = lp + (hb * 8 + e) * 2048; kf[e][0] = *(const h16x8*)(tp + ((fq ^ sw) << 4)); kf[e][1] = *(const h16x8*)(tp + (((fq + 4) ^ sw) << 4)); }
; #pragma unroll
;         for (int e = 0; e < 8; ++e) { const int T = Tbase + hb * 8 + e;
;             f32x4 a0 = (f32x4){0.f, 0.f, 0.f, 0.f}, a1 = a0;
;             a0 = __builtin_amdgcn_mfma_f32_16x16x32_f16(aq[0][0], kf[e][0], a0, 0, 0, 0); a0 = __builtin_amdgcn_mfma_f32_16x16x32_f16(aq[0][1], kf[e][1], a0, 0, 0, 0);
;             a1 = __builtin_amdgcn_mfma_f32_16x16x32_f16(aq[1][0], kf[e][0], a1, 0, 0, 0); a1 = __builtin_amdgcn_mfma_f32_16x16x32_f16(aq[1][1], kf[e][1], a1, 0, 0, 0);
;             const h16x2 z2 = (h16x2){(h16)0.f, (h16)0.f};
;             const h16x2 r0 = __builtin_elementwise_max(__builtin_bit_cast(h16x2, __builtin_amdgcn_cvt_pkrtz(a0[0], a0[1])), z2), r1 = __builtin_elementwise_max(__builtin_bit_cast(h16x2, __builtin_amdgcn_cvt_pkrtz(a0[2], a0[3])), z2);
;             const h16x2 r2 = __builtin_elementwise_max(__builtin_bit_cast(h16x2, __builtin_amdgcn_cvt_pkrtz(a1[0], a1[1])), z2), r3 = __builtin_elementwise_max(__builtin_bit_cast(h16x2, __builtin_amdgcn_cvt_pkrtz(a1[2], a1[3])), z2);
;             const float sa = __builtin_amdgcn_fdot2(r0, wp[0], __builtin_amdgcn_fdot2(r1, wp[1], __builtin_amdgcn_fdot2(r2, wp[2], __builtin_amdgcn_fdot2(r3, wp[3], 0.f, false), false), false), false);
;             const int key = 16 * T + fr;
;             if (key <= tq) {
;                 const unsigned bin = (unsigned)(int)fminf(fmaxf(sa * 32.f + 128.f, 0.f), 255.f);
;                 if (PASS == 1) { if (bin >= b0) atomicAdd(&myhist[fq * 256 + bin], 1u); }
	v_mfma_f32_16x16x32_f16 v[48:51], v[0:3], v[32:35], 0
	v_cvt_pkrtz_f16_f32 v67, v62, v63
	v_cvt_pkrtz_f16_f32 v66, v60, v61
	v_pk_max_f16 v67, v67, 0
	v_pk_max_f16 v66, v66, 0
	v_mfma_f32_16x16x32_f16 v[52:55], v[8:11], v[32:35], 0
	v_cvt_pkrtz_f16_f32 v65, v58, v59
	v_cvt_pkrtz_f16_f32 v64, v56, v57
	v_med3_f32 v76, v68, 0, v79
	v_pk_max_f16 v65, v65, 0
	v_mfma_f32_16x16x32_f16 v[48:51], v[4:7], v[36:39], v[48:51]
	v_pk_max_f16 v64, v64, 0
	v_cvt_u32_f32_e32 v76, v76
	v_cmp_le_i32_e32 vcc, -176, v78
	v_mfma_f32_16x16x32_f16 v[52:55], v[12:15], v[36:39], v[52:55]
	v_lshl_add_u32 v77, v76, 2, v139
	s_and_b64 exec, exec, vcc
	ds_add_u32 v77, v212
	s_mov_b64 exec, -1
	v_mfma_f32_16x16x32_f16 v[72:75], v[80:83], v[64:67], v[84:87]
	ds_read_b128 v[32:35], v122 offset:16384
	ds_read_b128 v[36:39], v123 offset:16384
	s_waitcnt lgkmcnt(3)
	v_mfma_f32_16x16x32_f16 v[56:59], v[0:3], v[40:43], 0
	v_cvt_pkrtz_f16_f32 v67, v54, v55
	v_cvt_pkrtz_f16_f32 v66, v52, v53
	v_pk_max_f16 v67, v67, 0
	v_pk_max_f16 v66, v66, 0
	v_mfma_f32_16x16x32_f16 v[60:63], v[8:11], v[40:43], 0
	v_cvt_pkrtz_f16_f32 v65, v50, v51
	v_cvt_pkrtz_f16_f32 v64, v48, v49
	v_med3_f32 v76, v72, 0, v79
	v_pk_max_f16 v65, v65, 0
	v_mfma_f32_16x16x32_f16 v[56:59], v[4:7], v[44:47], v[56:59]
	v_pk_max_f16 v64, v64, 0
	v_cvt_u32_f32_e32 v76, v76
	v_cmp_le_i32_e32 vcc, -160, v78
	v_mfma_f32_16x16x32_f16 v[60:63], v[12:15], v[44:47], v[60:63]
	v_lshl_add_u32 v77, v76, 2, v139
	s_and_b64 exec, exec, vcc
	ds_add_u32 v77, v212
	s_mov_b64 exec, -1
	v_mfma_f32_16x16x32_f16 v[68:71], v[80:83], v[64:67], v[84:87]
	ds_read_b128 v[40:43], v122 offset:18432
	ds_read_b128 v[44:47], v123 offset:18432
	s_waitcnt lgkmcnt(3)
	v_mfma_f32_16x16x32_f16 v[48:51], v[0:3], v[32:35], 0
	v_cvt_pkrtz_f16_f32 v67, v62, v63
	v_cvt_pkrtz_f16_f32 v66, v60, v61
	v_pk_max_f16 v67, v67, 0
	v_pk_max_f16 v66, v66, 0
	v_mfma_f32_16x16x32_f16 v[52:55], v[8:11], v[32:35], 0
	v_cvt_pkrtz_f16_f32 v65, v58, v59
	v_cvt_pkrtz_f16_f32 v64, v56, v57
	v_med3_f32 v76, v68, 0, v79
	v_pk_max_f16 v65, v65, 0
	v_mfma_f32_16x16x32_f16 v[48:51], v[4:7], v[36:39], v[48:51]
	v_pk_max_f16 v64, v64, 0
	v_cvt_u32_f32_e32 v76, v76
	v_cmp_le_i32_e32 vcc, -144, v78
	v_mfma_f32_16x16x32_f16 v[52:55], v[12:15], v[36:39], v[52:55]
	v_lshl_add_u32 v77, v76, 2, v139
	s_and_b64 exec, exec, vcc
	ds_add_u32 v77, v212
	s_mov_b64 exec, -1
	v_mfma_f32_16x16x32_f16 v[72:75], v[80:83], v[64:67], v[84:87]
	ds_read_b128 v[32:35], v122 offset:20480
	ds_read_b128 v[36:39], v123 offset:20480
	s_waitcnt lgkmcnt(3)
	v_mfma_f32_16x16x32_f16 v[56:59], v[0:3], v[40:43], 0
	v_cvt_pkrtz_f16_f32 v67, v54, v55
	v_cvt_pkrtz_f16_f32 v66, v52, v53
	v_pk_max_f16 v67, v67, 0
	v_pk_max_f16 v66, v66, 0
	v_mfma_f32_16x16x32_f16 v[60:63], v[8:11], v[40:43], 0
	v_cvt_pkrtz_f16_f32 v65, v50, v51
	v_cvt_pkrtz_f16_f32 v64, v48, v49
	v_med3_f32 v76, v72, 0, v79
	v_pk_max_f16 v65, v65, 0
	v_mfma_f32_16x16x32_f16 v[56:59], v[4:7], v[44:47], v[56:59]
	v_pk_max_f16 v64, v64, 0
	v_cvt_u32_f32_e32 v76, v76
	v_cmp_le_i32_e32 vcc, -128, v78
	v_mfma_f32_16x16x32_f16 v[60:63], v[12:15], v[44:47], v[60:63]
	v_lshl_add_u32 v77, v76, 2, v139
	s_and_b64 exec, exec, vcc
	ds_add_u32 v77, v212
	s_mov_b64 exec, -1
	v_mfma_f32_16x16x32_f16 v[68:71], v[80:83], v[64:67], v[84:87]
	ds_read_b128 v[40:43], v122 offset:22528
	ds_read_b128 v[44:47], v123 offset:22528
	s_waitcnt lgkmcnt(3)
	v_mfma_f32_16x16x32_f16 v[48:51], v[0:3], v[32:35], 0
	v_cvt_pkrtz_f16_f32 v67, v62, v63
	v_cvt_pkrtz_f16_f32 v66, v60, v61
	v_pk_max_f16 v67, v67, 0
	v_pk_max_f16 v66, v66, 0
	v_mfma_f32_16x16x32_f16 v[52:55], v[8:11], v[32:35], 0
	v_cvt_pkrtz_f16_f32 v65, v58, v59
	v_cvt_pkrtz_f16_f32 v64, v56, v57
	v_med3_f32 v76, v68, 0, v79
	v_pk_max_f16 v65, v65, 0
	v_mfma_f32_16x16x32_f16 v[48:51], v[4:7], v[36:39], v[48:51]
	v_pk_max_f16 v64, v64, 0
	v_cvt_u32_f32_e32 v76, v76
	v_cmp_le_i32_e32 vcc, -112, v78
	v_mfma_f32_16x16x32_f16 v[52:55], v[12:15], v[36:39], v[52:55]
	v_lshl_add_u32 v77, v76, 2, v139
	s_and_b64 exec, exec, vcc
	ds_add_u32 v77, v212
	s_mov_b64 exec, -1
	v_mfma_f32_16x16x32_f16 v[72:75], v[80:83], v[64:67], v[84:87]
	ds_read_b128 v[32:35], v122 offset:24576
	ds_read_b128 v[36:39], v123 offset:24576
	s_waitcnt lgkmcnt(3)
	v_mfma_f32_16x16x32_f16 v[56:59], v[0:3], v[40:43], 0
	v_cvt_pkrtz_f16_f32 v67, v54, v55
	v_cvt_pkrtz_f16_f32 v66, v52, v53
	v_pk_max_f16 v67, v67, 0
	v_pk_max_f16 v66, v66, 0
	v_mfma_f32_16x16x32_f16 v[60:63], v[8:11], v[40:43], 0
	v_cvt_pkrtz_f16_f32 v65, v50, v51
	v_cvt_pkrtz_f16_f32 v64, v48, v49
	v_med3_f32 v76, v72, 0, v79
	v_pk_max_f16 v65, v65, 0
	v_mfma_f32_16x16x32_f16 v[56:59], v[4:7], v[44:47], v[56:59]
	v_pk_max_f16 v64, v64, 0
	v_cvt_u32_f32_e32 v76, v76
	v_cmp_le_i32_e32 vcc, -96, v78
	v_mfma_f32_16x16x32_f16 v[60:63], v[12:15], v[44:47], v[60:63]
	v_lshl_add_u32 v77, v76, 2, v139
	s_and_b64 exec, exec, vcc
	ds_add_u32 v77, v212
	s_mov_b64 exec, -1
	v_mfma_f32_16x16x32_f16 v[68:71], v[80:83], v[64:67], v[84:87]
	ds_read_b128 v[40:43], v122 offset:26624
	ds_read_b128 v[44:47], v123 offset:26624
	s_waitcnt lgkmcnt(3)
	v_mfma_f32_16x16x32_f16 v[48:51], v[0:3], v[32:35], 0
	v_cvt_pkrtz_f16_f32 v67, v62, v63
	v_cvt_pkrtz_f16_f32 v66, v60, v61
	v_pk_max_f16 v67, v67, 0
	v_pk_max_f16 v66, v66, 0
	v_mfma_f32_16x16x32_f16 v[52:55], v[8:11], v[32:35], 0
	v_cvt_pkrtz_f16_f32 v65, v58, v59
	v_cvt_pkrtz_f16_f32 v64, v56, v57
	v_med3_f32 v76, v68, 0, v79
	v_pk_max_f16 v65, v65, 0
	v_mfma_f32_16x16x32_f16 v[48:51], v[4:7], v[36:39], v[48:51]
	v_pk_max_f16 v64, v64, 0
	v_cvt_u32_f32_e32 v76, v76
	v_cmp_le_i32_e32 vcc, -80, v78
	v_mfma_f32_16x16x32_f16 v[52:55], v[12:15], v[36:39], v[52:55]
	v_lshl_add_u32 v77, v76, 2, v139
	s_and_b64 exec, exec, vcc
	ds_add_u32 v77, v212
	s_mov_b64 exec, -1
	v_mfma_f32_16x16x32_f16 v[72:75], v[80:83], v[64:67], v[84:87]
	ds_read_b128 v[32:35], v122 offset:28672
	ds_read_b128 v[36:39], v123 offset:28672
	s_waitcnt lgkmcnt(3)
; template <int PASS> ...
;     ...
;         for (int e = 0; e < 8; ++e) { const unsigned char* tp = lp + (hb * 8 + e) * 2048; kf[e][0] = *(const h16x8*)(tp + ((fq ^ sw) << 4)); kf[e][1] = *(const h16x8*)(tp + (((fq + 4) ^ sw) << 4)); }
; #pragma unroll
;         for (int e = 0; e < 8; ++e) { const int T = Tbase + hb * 8 + e;
;             f32x4 a0 = (f32x4){0.f, 0.f, 0.f, 0.f}, a1 = a0;
;             a0 = __builtin_amdgcn_mfma_f32_16x16x32_f16(aq[0][0], kf[e][0], a0, 0, 0, 0); a0 = __builtin_amdgcn_mfma_f32_16x16x32_f16(aq[0][1], kf[e][1], a0, 0, 0, 0);
;             a1 = __builtin_amdgcn_mfma_f32_16x16x32_f16(aq[1][0], kf[e][0], a1, 0, 0, 0); a1 = __builtin_amdgcn_mfma_f32_16x16x32_f16(aq[1][1], kf[e][1], a1, 0, 0, 0);
;             const h16x2 z2 = (h16x2){(h16)0.f, (h16)0.f};
;             const h16x2 r0 = __builtin_elementwise_max(__builtin_bit_cast(h16x2, __builtin_amdgcn_cvt_pkrtz(a0[0], a0[1])), z2), r1 = __builtin_elementwise_max(__builtin_bit_cast(h16x2, __builtin_amdgcn_cvt_pkrtz(a0[2], a0[3])), z2);
;             const h16x2 r2 = __builtin_elementwise_max(__builtin_bit_cast(h16x2, __builtin_amdgcn_cvt_pkrtz(a1[0], a1[1])), z2), r3 = __builtin_elementwise_max(__builtin_bit_cast(h16x2, __builtin_amdgcn_cvt_pkrtz(a1[2], a1[3])), z2);
;             const float sa = __builtin_amdgcn_fdot2(r0, wp[0], __builtin_amdgcn_fdot2(r1, wp[1], __builtin_amdgcn_fdot2(r2, wp[2], __builtin_amdgcn_fdot2(r3, wp[3], 0.f, false), false), false), false);
;             const int key = 16 * T + fr;
;             if (key <= tq) {
;                 const unsigned bin = (unsigned)(int)fminf(fmaxf(sa * 32.f + 128.f, 0.f), 255.f);
;                 if (PASS == 1) { if (bin >= b0) atomicAdd(&myhist[fq * 256 + bin], 1u); }
; __device__ __forceinline__ void dsa_select(const h16* PROJ, unsigned short* IDX, int* CNT, unsigned char* shm, unsigned* bar, unsigned xcc, unsigned xrank) {
;     ...
;             float wv[8];
;             { const h16x8 w8 = *(const h16x8*)(PROJ + O_WI + (size_t)(tokbase + tq) * 8);
; #pragma unroll
;               for (int h = 0; h < 8; ++h) wv[h] = (float)w8[h] * 0.04419417382415922f; }
;             h16x2 wp[4];
; #pragma unroll
;             for (int h = 0; h < 4; ++h) { wp[h].x = (h16)wv[(h >> 1) * 4 + (h & 1) * 2]; wp[h].y = (h16)wv[(h >> 1) * 4 + (h & 1) * 2 + 1]; }
	v_mfma_f32_16x16x32_f16 v[56:59], v[0:3], v[40:43], 0
	v_cvt_pkrtz_f16_f32 v67, v54, v55
	v_cvt_pkrtz_f16_f32 v66, v52, v53
	v_pk_max_f16 v67, v67, 0
	v_pk_max_f16 v66, v66, 0
	v_mfma_f32_16x16x32_f16 v[60:63], v[8:11], v[40:43], 0
	v_cvt_pkrtz_f16_f32 v65, v50, v51
	v_cvt_pkrtz_f16_f32 v64, v48, v49
	v_med3_f32 v76, v72, 0, v79
	v_pk_max_f16 v65, v65, 0
	v_mfma_f32_16x16x32_f16 v[56:59], v[4:7], v[44:47], v[56:59]
	v_pk_max_f16 v64, v64, 0
	v_cvt_u32_f32_e32 v76, v76
	v_cmp_le_i32_e32 vcc, -64, v78
	v_mfma_f32_16x16x32_f16 v[60:63], v[12:15], v[44:47], v[60:63]
	v_lshl_add_u32 v77, v76, 2, v139
	s_and_b64 exec, exec, vcc
	ds_add_u32 v77, v212
	s_mov_b64 exec, -1
	v_mfma_f32_16x16x32_f16 v[68:71], v[80:83], v[64:67], v[84:87]
	ds_read_b128 v[40:43], v122 offset:30720
	ds_read_b128 v[44:47], v123 offset:30720
	s_waitcnt lgkmcnt(3)
	v_mfma_f32_16x16x32_f16 v[48:51], v[0:3], v[32:35], 0
	v_cvt_pkrtz_f16_f32 v67, v62, v63
	v_cvt_pkrtz_f16_f32 v66, v60, v61
	v_pk_max_f16 v67, v67, 0
	v_pk_max_f16 v66, v66, 0
	v_mfma_f32_16x16x32_f16 v[52:55], v[8:11], v[32:35], 0
	v_cvt_pkrtz_f16_f32 v65, v58, v59
	v_cvt_pkrtz_f16_f32 v64, v56, v57
	v_med3_f32 v76, v68, 0, v79
	v_pk_max_f16 v65, v65, 0
	v_mfma_f32_16x16x32_f16 v[48:51], v[4:7], v[36:39], v[48:51]
	v_pk_max_f16 v64, v64, 0
	v_cvt_u32_f32_e32 v76, v76
	v_cmp_le_i32_e32 vcc, -48, v78
	v_mfma_f32_16x16x32_f16 v[52:55], v[12:15], v[36:39], v[52:55]
	v_lshl_add_u32 v77, v76, 2, v139
	s_and_b64 exec, exec, vcc
	ds_add_u32 v77, v212
	s_mov_b64 exec, -1
	v_mfma_f32_16x16x32_f16 v[72:75], v[80:83], v[64:67], v[84:87]
	s_nop 3
	s_waitcnt lgkmcnt(1)
	v_mfma_f32_16x16x32_f16 v[56:59], v[0:3], v[40:43], 0
	v_cvt_pkrtz_f16_f32 v67, v54, v55
	v_cvt_pkrtz_f16_f32 v66, v52, v53
	v_pk_max_f16 v67, v67, 0
	v_pk_max_f16 v66, v66, 0
	v_mfma_f32_16x16x32_f16 v[60:63], v[8:11], v[40:43], 0
	v_cvt_pkrtz_f16_f32 v65, v50, v51
	v_cvt_pkrtz_f16_f32 v64, v48, v49
	v_med3_f32 v76, v72, 0, v79
	v_pk_max_f16 v65, v65, 0
	v_mfma_f32_16x16x32_f16 v[56:59], v[4:7], v[44:47], v[56:59]
	v_pk_max_f16 v64, v64, 0
	v_cvt_u32_f32_e32 v76, v76
	v_cmp_le_i32_e32 vcc, -32, v78
	v_mfma_f32_16x16x32_f16 v[60:63], v[12:15], v[44:47], v[60:63]
	v_lshl_add_u32 v77, v76, 2, v139
	s_and_b64 exec, exec, vcc
	ds_add_u32 v77, v212
	s_mov_b64 exec, -1
	v_mfma_f32_16x16x32_f16 v[68:71], v[80:83], v[64:67], v[84:87]
	s_nop 3
	v_cvt_pkrtz_f16_f32 v67, v62, v63
	v_cvt_pkrtz_f16_f32 v66, v60, v61
	v_pk_max_f16 v67, v67, 0
	v_pk_max_f16 v66, v66, 0
	v_cvt_pkrtz_f16_f32 v65, v58, v59
	v_cvt_pkrtz_f16_f32 v64, v56, v57
	v_med3_f32 v76, v68, 0, v79
	v_pk_max_f16 v65, v65, 0
	v_pk_max_f16 v64, v64, 0
	v_cvt_u32_f32_e32 v76, v76
	v_cmp_le_i32_e32 vcc, -16, v78
	v_lshl_add_u32 v77, v76, 2, v139
	s_and_b64 exec, exec, vcc
	ds_add_u32 v77, v212
	s_mov_b64 exec, -1
	v_mfma_f32_16x16x32_f16 v[72:75], v[80:83], v[64:67], v[84:87]
	s_nop 7
	s_nop 3
	v_med3_f32 v76, v72, 0, v79
	v_cvt_u32_f32_e32 v76, v76
	v_cmp_le_i32_e32 vcc, 0, v78
	v_lshl_add_u32 v77, v76, 2, v139
	s_and_b64 exec, exec, vcc
	ds_add_u32 v77, v212
	s_mov_b64 exec, -1
	s_branch .LBB0_239
.Lp1_interior:
	ds_read_b128 v[32:35], v122
	ds_read_b128 v[36:39], v123
	ds_read_b128 v[40:43], v122 offset:2048
	ds_read_b128 v[44:47], v123 offset:2048
	v_mov_b32_e32 v79, 0x437f0000
	v_mul_f32_e32 v88, v106, v106
	v_fmac_f32_e32 v88, v107, v107
	v_fmac_f32_e32 v88, v108, v108
	v_fmac_f32_e32 v88, v109, v109
	v_fmac_f32_e32 v88, v110, v110
	v_fmac_f32_e32 v88, v111, v111
	v_fmac_f32_e32 v88, v112, v112
	v_fmac_f32_e32 v88, v113, v113
	v_max_f32_e32 v88, 0x358637bd, v88
	v_rsq_f32_e32 v88, v88
	s_mov_b32 s62, 0x100001
	s_mov_b32 s63, 0x10000100
	v_mul_f32_e32 v88, 4.0, v88
	v_cvt_pkrtz_f16_f32 v88, v88, v88
	v_pk_mul_f16 v80, v193, v88
	v_pk_mul_f16 v81, v194, v88
	v_pk_mul_f16 v82, v195, v88
	v_pk_mul_f16 v83, v196, v88
	v_cndmask_b32_e64 v80, 0, v80, s[62:63]
	v_cndmask_b32_e64 v81, 0, v81, s[62:63]
	v_cndmask_b32_e64 v82, 0, v82, s[62:63]
	v_cndmask_b32_e64 v83, 0, v83, s[62:63]
	v_mov_b32_e32 v84, 0x43000000
	v_mov_b32_e32 v85, 0
	v_mov_b32_e32 v86, 0
	v_mov_b32_e32 v87, 0
	s_waitcnt lgkmcnt(2)
	v_mfma_f32_16x16x32_f16 v[48:51], v[0:3], v[32:35], 0
	v_mfma_f32_16x16x32_f16 v[52:55], v[8:11], v[32:35], 0
	v_mfma_f32_16x16x32_f16 v[48:51], v[4:7], v[36:39], v[48:51]
	v_mfma_f32_16x16x32_f16 v[52:55], v[12:15], v[36:39], v[52:55]
	s_nop 3
	ds_read_b128 v[32:35], v122 offset:4096
	ds_read_b128 v[36:39], v123 offset:4096
	s_waitcnt lgkmcnt(2)
	v_mfma_f32_16x16x32_f16 v[56:59], v[0:3], v[40:43], 0
	v_cvt_pkrtz_f16_f32 v67, v54, v55
	v_cvt_pkrtz_f16_f32 v66, v52, v53
	v_pk_max_f16 v67, v67, 0
	v_pk_max_f16 v66, v66, 0
	v_mfma_f32_16x16x32_f16 v[60:63], v[8:11], v[40:43], 0
	v_cvt_pkrtz_f16_f32 v65, v50, v51
	v_cvt_pkrtz_f16_f32 v64, v48, v49
	v_pk_max_f16 v65, v65, 0
	v_mfma_f32_16x16x32_f16 v[56:59], v[4:7], v[44:47], v[56:59]
	v_pk_max_f16 v64, v64, 0
	v_mfma_f32_16x16x32_f16 v[60:63], v[12:15], v[44:47], v[60:63]
	s_nop 3
	v_mfma_f32_16x16x32_f16 v[68:71], v[80:83], v[64:67], v[84:87]
	ds_read_b128 v[40:43], v122 offset:6144
	ds_read_b128 v[44:47], v123 offset:6144
	s_waitcnt lgkmcnt(2)
	v_mfma_f32_16x16x32_f16 v[48:51], v[0:3], v[32:35], 0
	v_cvt_pkrtz_f16_f32 v67, v62, v63
	v_cvt_pkrtz_f16_f32 v66, v60, v61
	v_pk_max_f16 v67, v67, 0
	v_pk_max_f16 v66, v66, 0
	v_mfma_f32_16x16x32_f16 v[52:55], v[8:11], v[32:35], 0
	v_cvt_pkrtz_f16_f32 v65, v58, v59
	v_cvt_pkrtz_f16_f32 v64, v56, v57
	v_med3_f32 v76, v68, 0, v79
	v_pk_max_f16 v65, v65, 0
	v_mfma_f32_16x16x32_f16 v[48:51], v[4:7], v[36:39], v[48:51]
	v_pk_max_f16 v64, v64, 0
	v_cvt_u32_f32_e32 v76, v76
	v_mfma_f32_16x16x32_f16 v[52:55], v[12:15], v[36:39], v[52:55]
	v_lshl_add_u32 v77, v76, 2, v139
	s_nop 0
	ds_add_u32 v77, v212
	s_nop 0
	s_nop 0
	v_mfma_f32_16x16x32_f16 v[72:75], v[80:83], v[64:67], v[84:87]
	ds_read_b128 v[32:35], v122 offset:8192
	ds_read_b128 v[36:39], v123 offset:8192
	s_waitcnt lgkmcnt(3)
; template <int PASS> ...
;     ...
;         for (int e = 0; e < 8; ++e) { const unsigned char* tp = lp + (hb * 8 + e) * 2048; kf[e][0] = *(const h16x8*)(tp + ((fq ^ sw) << 4)); kf[e][1] = *(const h16x8*)(tp + (((fq + 4) ^ sw) << 4)); }
; #pragma unroll
;         for (int e = 0; e < 8; ++e) { const int T = Tbase + hb * 8 + e;
;             f32x4 a0 = (f32x4){0.f, 0.f, 0.f, 0.f}, a1 = a0;
;             a0 = __builtin_amdgcn_mfma_f32_16x16x32_f16(aq[0][0], kf[e][0], a0, 0, 0, 0); a0 = __builtin_amdgcn_mfma_f32_16x16x32_f16(aq[0][1], kf[e][1], a0, 0, 0, 0);
;             a1 = __builtin_amdgcn_mfma_f32_16x16x32_f16(aq[1][0], kf[e][0], a1, 0, 0, 0); a1 = __builtin_amdgcn_mfma_f32_16x16x32_f16(aq[1][1], kf[e][1], a1, 0, 0, 0);
;             const h16x2 z2 = (h16x2){(h16)0.f, (h16)0.f};
;             const h16x2 r0 = __builtin_elementwise_max(__builtin_bit_cast(h16x2, __builtin_amdgcn_cvt_pkrtz(a0[0], a0[1])), z2), r1 = __builtin_elementwise_max(__builtin_bit_cast(h16x2, __builtin_amdgcn_cvt_pkrtz(a0[2], a0[3])), z2);
;             const h16x2 r2 = __builtin_elementwise_max(__builtin_bit_cast(h16x2, __builtin_amdgcn_cvt_pkrtz(a1[0], a1[1])), z2), r3 = __builtin_elementwise_max(__builtin_bit_cast(h16x2, __builtin_amdgcn_cvt_pkrtz(a1[2], a1[3])), z2);
;             const float sa = __builtin_amdgcn_fdot2(r0, wp[0], __builtin_amdgcn_fdot2(r1, wp[1], __builtin_amdgcn_fdot2(r2, wp[2], __builtin_amdgcn_fdot2(r3, wp[3], 0.f, false), false), false), false);
;             const int key = 16 * T + fr;
;             if (key <= tq) {
;                 const unsigned bin = (unsigned)(int)fminf(fmaxf(sa * 32.f + 128.f, 0.f), 255.f);
;                 if (PASS == 1) { if (bin >= b0) atomicAdd(&myhist[fq * 256 + bin], 1u); }
	v_mfma_f32_16x16x32_f16 v[56:59], v[0:3], v[40:43], 0
	v_cvt_pkrtz_f16_f32 v67, v54, v55
	v_cvt_pkrtz_f16_f32 v66, v52, v53
	v_pk_max_f16 v67, v67, 0
	v_pk_max_f16 v66, v66, 0
	v_mfma_f32_16x16x32_f16 v[60:63], v[8:11], v[40:43], 0
	v_cvt_pkrtz_f16_f32 v65, v50, v51
	v_cvt_pkrtz_f16_f32 v64, v48, v49
	v_med3_f32 v76, v72, 0, v79
	v_pk_max_f16 v65, v65, 0
	v_mfma_f32_16x16x32_f16 v[56:59], v[4:7], v[44:47], v[56:59]
	v_pk_max_f16 v64, v64, 0
	v_cvt_u32_f32_e32 v76, v76
	v_mfma_f32_16x16x32_f16 v[60:63], v[12:15], v[44:47], v[60:63]
	v_lshl_add_u32 v77, v76, 2, v139
	s_nop 0
	ds_add_u32 v77, v212
	s_nop 0
	s_nop 0
	v_mfma_f32_16x16x32_f16 v[68:71], v[80:83], v[64:67], v[84:87]
	ds_read_b128 v[40:43], v122 offset:10240
	ds_read_b128 v[44:47], v123 offset:10240
	s_waitcnt lgkmcnt(3)
	v_mfma_f32_16x16x32_f16 v[48:51], v[0:3], v[32:35], 0
	v_cvt_pkrtz_f16_f32 v67, v62, v63
	v_cvt_pkrtz_f16_f32 v66, v60, v61
	v_pk_max_f16 v67, v67, 0
	v_pk_max_f16 v66, v66, 0
	v_mfma_f32_16x16x32_f16 v[52:55], v[8:11], v[32:35], 0
	v_cvt_pkrtz_f16_f32 v65, v58, v59
	v_cvt_pkrtz_f16_f32 v64, v56, v57
	v_med3_f32 v76, v68, 0, v79
	v_pk_max_f16 v65, v65, 0
	v_mfma_f32_16x16x32_f16 v[48:51], v[4:7], v[36:39], v[48:51]
	v_pk_max_f16 v64, v64, 0
	v_cvt_u32_f32_e32 v76, v76
	v_mfma_f32_16x16x32_f16 v[52:55], v[12:15], v[36:39], v[52:55]
	v_lshl_add_u32 v77, v76, 2, v139
	s_nop 0
	ds_add_u32 v77, v212
	s_nop 0
	s_nop 0
	v_mfma_f32_16x16x32_f16 v[72:75], v[80:83], v[64:67], v[84:87]
	ds_read_b128 v[32:35], v122 offset:12288
	ds_read_b128 v[36:39], v123 offset:12288
	s_waitcnt lgkmcnt(3)
	v_mfma_f32_16x16x32_f16 v[56:59], v[0:3], v[40:43], 0
	v_cvt_pkrtz_f16_f32 v67, v54, v55
	v_cvt_pkrtz_f16_f32 v66, v52, v53
	v_pk_max_f16 v67, v67, 0
	v_pk_max_f16 v66, v66, 0
	v_mfma_f32_16x16x32_f16 v[60:63], v[8:11], v[40:43], 0
	v_cvt_pkrtz_f16_f32 v65, v50, v51
	v_cvt_pkrtz_f16_f32 v64, v48, v49
	v_med3_f32 v76, v72, 0, v79
	v_pk_max_f16 v65, v65, 0
	v_mfma_f32_16x16x32_f16 v[56:59], v[4:7], v[44:47], v[56:59]
	v_pk_max_f16 v64, v64, 0
	v_cvt_u32_f32_e32 v76, v76
	v_mfma_f32_16x16x32_f16 v[60:63], v[12:15], v[44:47], v[60:63]
	v_lshl_add_u32 v77, v76, 2, v139
	s_nop 0
	ds_add_u32 v77, v212
	s_nop 0
	s_nop 0
	v_mfma_f32_16x16x32_f16 v[68:71], v[80:83], v[64:67], v[84:87]
	ds_read_b128 v[40:43], v122 offset:14336
	ds_read_b128 v[44:47], v123 offset:14336
	s_waitcnt lgkmcnt(3)
	v_mfma_f32_16x16x32_f16 v[48:51], v[0:3], v[32:35], 0
	v_cvt_pkrtz_f16_f32 v67, v62, v63
	v_cvt_pkrtz_f16_f32 v66, v60, v61
	v_pk_max_f16 v67, v67, 0
	v_pk_max_f16 v66, v66, 0
	v_mfma_f32_16x16x32_f16 v[52:55], v[8:11], v[32:35], 0
	v_cvt_pkrtz_f16_f32 v65, v58, v59
	v_cvt_pkrtz_f16_f32 v64, v56, v57
	v_med3_f32 v76, v68, 0, v79
	v_pk_max_f16 v65, v65, 0
	v_mfma_f32_16x16x32_f16 v[48:51], v[4:7], v[36:39], v[48:51]
	v_pk_max_f16 v64, v64, 0
	v_cvt_u32_f32_e32 v76, v76
	v_mfma_f32_16x16x32_f16 v[52:55], v[12:15], v[36:39], v[52:55]
	v_lshl_add_u32 v77, v76, 2, v139
	s_nop 0
	ds_add_u32 v77, v212
	s_nop 0
	s_nop 0
	v_mfma_f32_16x16x32_f16 v[72:75], v[80:83], v[64:67], v[84:87]
	ds_read_b128 v[32:35], v122 offset:16384
	ds_read_b128 v[36:39], v123 offset:16384
	s_waitcnt lgkmcnt(3)
	v_mfma_f32_16x16x32_f16 v[56:59], v[0:3], v[40:43], 0
	v_cvt_pkrtz_f16_f32 v67, v54, v55
	v_cvt_pkrtz_f16_f32 v66, v52, v53
	v_pk_max_f16 v67, v67, 0
	v_pk_max_f16 v66, v66, 0
	v_mfma_f32_16x16x32_f16 v[60:63], v[8:11], v[40:43], 0
	v_cvt_pkrtz_f16_f32 v65, v50, v51
	v_cvt_pkrtz_f16_f32 v64, v48, v49
	v_med3_f32 v76, v72, 0, v79
	v_pk_max_f16 v65, v65, 0
	v_mfma_f32_16x16x32_f16 v[56:59], v[4:7], v[44:47], v[56:59]
	v_pk_max_f16 v64, v64, 0
	v_cvt_u32_f32_e32 v76, v76
	v_mfma_f32_16x16x32_f16 v[60:63], v[12:15], v[44:47], v[60:63]
	v_lshl_add_u32 v77, v76, 2, v139
	s_nop 0
	ds_add_u32 v77, v212
	s_nop 0
	s_nop 0
	v_mfma_f32_16x16x32_f16 v[68:71], v[80:83], v[64:67], v[84:87]
	ds_read_b128 v[40:43], v122 offset:18432
	ds_read_b128 v[44:47], v123 offset:18432
	s_waitcnt lgkmcnt(3)
	v_mfma_f32_16x16x32_f16 v[48:51], v[0:3], v[32:35], 0
	v_cvt_pkrtz_f16_f32 v67, v62, v63
	v_cvt_pkrtz_f16_f32 v66, v60, v61
	v_pk_max_f16 v67, v67, 0
	v_pk_max_f16 v66, v66, 0
	v_mfma_f32_16x16x32_f16 v[52:55], v[8:11], v[32:35], 0
	v_cvt_pkrtz_f16_f32 v65, v58, v59
	v_cvt_pkrtz_f16_f32 v64, v56, v57
	v_med3_f32 v76, v68, 0, v79
	v_pk_max_f16 v65, v65, 0
	v_mfma_f32_16x16x32_f16 v[48:51], v[4:7], v[36:39], v[48:51]
	v_pk_max_f16 v64, v64, 0
	v_cvt_u32_f32_e32 v76, v76
	v_mfma_f32_16x16x32_f16 v[52:55], v[12:15], v[36:39], v[52:55]
	v_lshl_add_u32 v77, v76, 2, v139
	s_nop 0
	ds_add_u32 v77, v212
	s_nop 0
	s_nop 0
	v_mfma_f32_16x16x32_f16 v[72:75], v[80:83], v[64:67], v[84:87]
	ds_read_b128 v[32:35], v122 offset:20480
	ds_read_b128 v[36:39], v123 offset:20480
	s_waitcnt lgkmcnt(3)
	v_mfma_f32_16x16x32_f16 v[56:59], v[0:3], v[40:43], 0
	v_cvt_pkrtz_f16_f32 v67, v54, v55
	v_cvt_pkrtz_f16_f32 v66, v52, v53
	v_pk_max_f16 v67, v67, 0
	v_pk_max_f16 v66, v66, 0
	v_mfma_f32_16x16x32_f16 v[60:63], v[8:11], v[40:43], 0
	v_cvt_pkrtz_f16_f32 v65, v50, v51
	v_cvt_pkrtz_f16_f32 v64, v48, v49
	v_med3_f32 v76, v72, 0, v79
	v_pk_max_f16 v65, v65, 0
	v_mfma_f32_16x16x32_f16 v[56:59], v[4:7], v[44:47], v[56:59]
	v_pk_max_f16 v64, v64, 0
	v_cvt_u32_f32_e32 v76, v76
	v_mfma_f32_16x16x32_f16 v[60:63], v[12:15], v[44:47], v[60:63]
	v_lshl_add_u32 v77, v76, 2, v139
	s_nop 0
	ds_add_u32 v77, v212
	s_nop 0
	s_nop 0
	v_mfma_f32_16x16x32_f16 v[68:71], v[80:83], v[64:67], v[84:87]
	ds_read_b128 v[40:43], v122 offset:22528
	ds_read_b128 v[44:47], v123 offset:22528
	s_waitcnt lgkmcnt(3)
; template <int PASS> ...
;     ...
;         for (int e = 0; e < 8; ++e) { const unsigned char* tp = lp + (hb * 8 + e) * 2048; kf[e][0] = *(const h16x8*)(tp + ((fq ^ sw) << 4)); kf[e][1] = *(const h16x8*)(tp + (((fq + 4) ^ sw) << 4)); }
; #pragma unroll
;         for (int e = 0; e < 8; ++e) { const int T = Tbase + hb * 8 + e;
;             f32x4 a0 = (f32x4){0.f, 0.f, 0.f, 0.f}, a1 = a0;
;             a0 = __builtin_amdgcn_mfma_f32_16x16x32_f16(aq[0][0], kf[e][0], a0, 0, 0, 0); a0 = __builtin_amdgcn_mfma_f32_16x16x32_f16(aq[0][1], kf[e][1], a0, 0, 0, 0);
;             a1 = __builtin_amdgcn_mfma_f32_16x16x32_f16(aq[1][0], kf[e][0], a1, 0, 0, 0); a1 = __builtin_amdgcn_mfma_f32_16x16x32_f16(aq[1][1], kf[e][1], a1, 0, 0, 0);
;             const h16x2 z2 = (h16x2){(h16)0.f, (h16)0.f};
;             const h16x2 r0 = __builtin_elementwise_max(__builtin_bit_cast(h16x2, __builtin_amdgcn_cvt_pkrtz(a0[0], a0[1])), z2), r1 = __builtin_elementwise_max(__builtin_bit_cast(h16x2, __builtin_amdgcn_cvt_pkrtz(a0[2], a0[3])), z2);
;             const h16x2 r2 = __builtin_elementwise_max(__builtin_bit_cast(h16x2, __builtin_amdgcn_cvt_pkrtz(a1[0], a1[1])), z2), r3 = __builtin_elementwise_max(__builtin_bit_cast(h16x2, __builtin_amdgcn_cvt_pkrtz(a1[2], a1[3])), z2);
;             const float sa = __builtin_amdgcn_fdot2(r0, wp[0], __builtin_amdgcn_fdot2(r1, wp[1], __builtin_amdgcn_fdot2(r2, wp[2], __builtin_amdgcn_fdot2(r3, wp[3], 0.f, false), false), false), false);
;             const int key = 16 * T + fr;
;             if (key <= tq) {
;                 const unsigned bin = (unsigned)(int)fminf(fmaxf(sa * 32.f + 128.f, 0.f), 255.f);
;                 if (PASS == 1) { if (bin >= b0) atomicAdd(&myhist[fq * 256 + bin], 1u); }
	v_mfma_f32_16x16x32_f16 v[48:51], v[0:3], v[32:35], 0
	v_cvt_pkrtz_f16_f32 v67, v62, v63
	v_cvt_pkrtz_f16_f32 v66, v60, v61
	v_pk_max_f16 v67, v67, 0
	v_pk_max_f16 v66, v66, 0
	v_mfma_f32_16x16x32_f16 v[52:55], v[8:11], v[32:35], 0
	v_cvt_pkrtz_f16_f32 v65, v58, v59
	v_cvt_pkrtz_f16_f32 v64, v56, v57
	v_med3_f32 v76, v68, 0, v79
	v_pk_max_f16 v65, v65, 0
	v_mfma_f32_16x16x32_f16 v[48:51], v[4:7], v[36:39], v[48:51]
	v_pk_max_f16 v64, v64, 0
	v_cvt_u32_f32_e32 v76, v76
	v_mfma_f32_16x16x32_f16 v[52:55], v[12:15], v[36:39], v[52:55]
	v_lshl_add_u32 v77, v76, 2, v139
	s_nop 0
	ds_add_u32 v77, v212
	s_nop 0
	s_nop 0
	v_mfma_f32_16x16x32_f16 v[72:75], v[80:83], v[64:67], v[84:87]
	ds_read_b128 v[32:35], v122 offset:24576
	ds_read_b128 v[36:39], v123 offset:24576
	s_waitcnt lgkmcnt(3)
	v_mfma_f32_16x16x32_f16 v[56:59], v[0:3], v[40:43], 0
	v_cvt_pkrtz_f16_f32 v67, v54, v55
	v_cvt_pkrtz_f16_f32 v66, v52, v53
	v_pk_max_f16 v67, v67, 0
	v_pk_max_f16 v66, v66, 0
	v_mfma_f32_16x16x32_f16 v[60:63], v[8:11], v[40:43], 0
	v_cvt_pkrtz_f16_f32 v65, v50, v51
	v_cvt_pkrtz_f16_f32 v64, v48, v49
	v_med3_f32 v76, v72, 0, v79
	v_pk_max_f16 v65, v65, 0
	v_mfma_f32_16x16x32_f16 v[56:59], v[4:7], v[44:47], v[56:59]
	v_pk_max_f16 v64, v64, 0
	v_cvt_u32_f32_e32 v76, v76
	v_mfma_f32_16x16x32_f16 v[60:63], v[12:15], v[44:47], v[60:63]
	v_lshl_add_u32 v77, v76, 2, v139
	s_nop 0
	ds_add_u32 v77, v212
	s_nop 0
	s_nop 0
	v_mfma_f32_16x16x32_f16 v[68:71], v[80:83], v[64:67], v[84:87]
	ds_read_b128 v[40:43], v122 offset:26624
	ds_read_b128 v[44:47], v123 offset:26624
	s_waitcnt lgkmcnt(3)
	v_mfma_f32_16x16x32_f16 v[48:51], v[0:3], v[32:35], 0
	v_cvt_pkrtz_f16_f32 v67, v62, v63
	v_cvt_pkrtz_f16_f32 v66, v60, v61
	v_pk_max_f16 v67, v67, 0
	v_pk_max_f16 v66, v66, 0
	v_mfma_f32_16x16x32_f16 v[52:55], v[8:11], v[32:35], 0
	v_cvt_pkrtz_f16_f32 v65, v58, v59
	v_cvt_pkrtz_f16_f32 v64, v56, v57
	v_med3_f32 v76, v68, 0, v79
	v_pk_max_f16 v65, v65, 0
	v_mfma_f32_16x16x32_f16 v[48:51], v[4:7], v[36:39], v[48:51]
	v_pk_max_f16 v64, v64, 0
	v_cvt_u32_f32_e32 v76, v76
	v_mfma_f32_16x16x32_f16 v[52:55], v[12:15], v[36:39], v[52:55]
	v_lshl_add_u32 v77, v76, 2, v139
	s_nop 0
	ds_add_u32 v77, v212
	s_nop 0
	s_nop 0
	v_mfma_f32_16x16x32_f16 v[72:75], v[80:83], v[64:67], v[84:87]
	ds_read_b128 v[32:35], v122 offset:28672
	ds_read_b128 v[36:39], v123 offset:28672
	s_waitcnt lgkmcnt(3)
	v_mfma_f32_16x16x32_f16 v[56:59], v[0:3], v[40:43], 0
	v_cvt_pkrtz_f16_f32 v67, v54, v55
	v_cvt_pkrtz_f16_f32 v66, v52, v53
	v_pk_max_f16 v67, v67, 0
	v_pk_max_f16 v66, v66, 0
	v_mfma_f32_16x16x32_f16 v[60:63], v[8:11], v[40:43], 0
	v_cvt_pkrtz_f16_f32 v65, v50, v51
	v_cvt_pkrtz_f16_f32 v64, v48, v49
	v_med3_f32 v76, v72, 0, v79
	v_pk_max_f16 v65, v65, 0
	v_mfma_f32_16x16x32_f16 v[56:59], v[4:7], v[44:47], v[56:59]
	v_pk_max_f16 v64, v64, 0
	v_cvt_u32_f32_e32 v76, v76
	v_mfma_f32_16x16x32_f16 v[60:63], v[12:15], v[44:47], v[60:63]
	v_lshl_add_u32 v77, v76, 2, v139
	s_nop 0
	ds_add_u32 v77, v212
	s_nop 0
	s_nop 0
	v_mfma_f32_16x16x32_f16 v[68:71], v[80:83], v[64:67], v[84:87]
	ds_read_b128 v[40:43], v122 offset:30720
	ds_read_b128 v[44:47], v123 offset:30720
	s_waitcnt lgkmcnt(3)
	v_mfma_f32_16x16x32_f16 v[48:51], v[0:3], v[32:35], 0
	v_cvt_pkrtz_f16_f32 v67, v62, v63
	v_cvt_pkrtz_f16_f32 v66, v60, v61
	v_pk_max_f16 v67, v67, 0
	v_pk_max_f16 v66, v66, 0
	v_mfma_f32_16x16x32_f16 v[52:55], v[8:11], v[32:35], 0
	v_cvt_pkrtz_f16_f32 v65, v58, v59
	v_cvt_pkrtz_f16_f32 v64, v56, v57
	v_med3_f32 v76, v68, 0, v79
	v_pk_max_f16 v65, v65, 0
	v_mfma_f32_16x16x32_f16 v[48:51], v[4:7], v[36:39], v[48:51]
	v_pk_max_f16 v64, v64, 0
	v_cvt_u32_f32_e32 v76, v76
	v_mfma_f32_16x16x32_f16 v[52:55], v[12:15], v[36:39], v[52:55]
	v_lshl_add_u32 v77, v76, 2, v139
	s_nop 0
	ds_add_u32 v77, v212
	s_nop 0
	s_nop 0
	v_mfma_f32_16x16x32_f16 v[72:75], v[80:83], v[64:67], v[84:87]
	s_nop 3
	s_waitcnt lgkmcnt(1)
	v_mfma_f32_16x16x32_f16 v[56:59], v[0:3], v[40:43], 0
	v_cvt_pkrtz_f16_f32 v67, v54, v55
	v_cvt_pkrtz_f16_f32 v66, v52, v53
	v_pk_max_f16 v67, v67, 0
	v_pk_max_f16 v66, v66, 0
	v_mfma_f32_16x16x32_f16 v[60:63], v[8:11], v[40:43], 0
	v_cvt_pkrtz_f16_f32 v65, v50, v51
	v_cvt_pkrtz_f16_f32 v64, v48, v49
	v_med3_f32 v76, v72, 0, v79
	v_pk_max_f16 v65, v65, 0
	v_mfma_f32_16x16x32_f16 v[56:59], v[4:7], v[44:47], v[56:59]
	v_pk_max_f16 v64, v64, 0
	v_cvt_u32_f32_e32 v76, v76
	v_mfma_f32_16x16x32_f16 v[60:63], v[12:15], v[44:47], v[60:63]
	v_lshl_add_u32 v77, v76, 2, v139
	s_nop 0
	ds_add_u32 v77, v212
	s_nop 0
	s_nop 0
	v_mfma_f32_16x16x32_f16 v[68:71], v[80:83], v[64:67], v[84:87]
	s_nop 3
	v_cvt_pkrtz_f16_f32 v67, v62, v63
	v_cvt_pkrtz_f16_f32 v66, v60, v61
	v_pk_max_f16 v67, v67, 0
	v_pk_max_f16 v66, v66, 0
	v_cvt_pkrtz_f16_f32 v65, v58, v59
	v_cvt_pkrtz_f16_f32 v64, v56, v57
	v_med3_f32 v76, v68, 0, v79
	v_pk_max_f16 v65, v65, 0
	v_pk_max_f16 v64, v64, 0
	v_cvt_u32_f32_e32 v76, v76
	v_lshl_add_u32 v77, v76, 2, v139
	s_nop 0
	ds_add_u32 v77, v212
	s_nop 0
	s_nop 0
	v_mfma_f32_16x16x32_f16 v[72:75], v[80:83], v[64:67], v[84:87]
	s_nop 7
	s_nop 3
	v_med3_f32 v76, v72, 0, v79
	v_cvt_u32_f32_e32 v76, v76
	v_lshl_add_u32 v77, v76, 2, v139
	s_nop 0
	ds_add_u32 v77, v212
	s_nop 0
	s_nop 0
	s_branch .LBB0_239

; template <int PASS> ...
;     ...
;         for (int e = 0; e < 8; ++e) { const int T = Tbase + hb * 8 + e;
;             f32x4 a0 = (f32x4){0.f, 0.f, 0.f, 0.f}, a1 = a0;
;             a0 = __builtin_amdgcn_mfma_f32_16x16x32_f16(aq[0][0], kf[e][0], a0, 0, 0, 0); a0 = __builtin_amdgcn_mfma_f32_16x16x32_f16(aq[0][1], kf[e][1], a0, 0, 0, 0);
;             a1 = __builtin_amdgcn_mfma_f32_16x16x32_f16(aq[1][0], kf[e][0], a1, 0, 0, 0); a1 = __builtin_amdgcn_mfma_f32_16x16x32_f16(aq[1][1], kf[e][1], a1, 0, 0, 0);
;             const h16x2 z2 = (h16x2){(h16)0.f, (h16)0.f};
;             const h16x2 r0 = __builtin_elementwise_max(__builtin_bit_cast(h16x2, __builtin_amdgcn_cvt_pkrtz(a0[0], a0[1])), z2), r1 = __builtin_elementwise_max(__builtin_bit_cast(h16x2, __builtin_amdgcn_cvt_pkrtz(a0[2], a0[3])), z2);
;             const h16x2 r2 = __builtin_elementwise_max(__builtin_bit_cast(h16x2, __builtin_amdgcn_cvt_pkrtz(a1[0], a1[1])), z2), r3 = __builtin_elementwise_max(__builtin_bit_cast(h16x2, __builtin_amdgcn_cvt_pkrtz(a1[2], a1[3])), z2);
;             const float sa = __builtin_amdgcn_fdot2(r0, wp[0], __builtin_amdgcn_fdot2(r1, wp[1], __builtin_amdgcn_fdot2(r2, wp[2], __builtin_amdgcn_fdot2(r3, wp[3], 0.f, false), false), false), false);
;             const int key = 16 * T + fr;
;             if (key <= tq) {
;                 const unsigned bin = (unsigned)(int)fminf(fmaxf(sa * 32.f + 128.f, 0.f), 255.f);
;                 if (PASS == 1) { if (bin >= b0) atomicAdd(&myhist[fq * 256 + bin], 1u); }
;                 else {
;                     if (bin > b0) { const unsigned pos = atomicAdd(&myctl[fq * 4 + 2], 1u); ((unsigned short*)myhist)[fq * 256 + (pos & 255u)] = (unsigned short)key; }
;                     else if (bin == b0) { const unsigned c = atomicAdd(&myctl[fq * 4 + 3], 1u);
; __device__ __forceinline__ void dsa_select(const h16* PROJ, unsigned short* IDX, int* CNT, unsigned char* shm, unsigned* bar, unsigned xcc, unsigned xrank) {
;     ...
;             float wv[8];
;             { const h16x8 w8 = *(const h16x8*)(PROJ + O_WI + (size_t)(tokbase + tq) * 8);
; #pragma unroll
;               for (int h = 0; h < 8; ++h) wv[h] = (float)w8[h] * 0.04419417382415922f; }
;             h16x2 wp[4];
; #pragma unroll
;             for (int h = 0; h < 4; ++h) { wp[h].x = (h16)wv[(h >> 1) * 4 + (h & 1) * 2]; wp[h].y = (h16)wv[(h >> 1) * 4 + (h & 1) * 2 + 1]; }
.LBB0_293:
	s_and_b32 s4, s85, 0x8000
	v_add_u32_e32 v72, s4, v134
	v_add_u32_e32 v118, v72, v135
	v_add_u32_e32 v119, v72, v136
	ds_read_b128 v[32:35], v118
	ds_read_b128 v[36:39], v119
	ds_read_b128 v[40:43], v118 offset:2048
	ds_read_b128 v[44:47], v119 offset:2048
	v_lshlrev_b32_e32 v116, 8, v116
	v_sub_u32_e32 v117, v121, v116
	v_sub_u32_e32 v93, v192, v117
	v_cvt_f32_u32_e32 v94, v120
	v_cmp_eq_u32_e32 vcc, 0, v120
	v_add_f32_e32 v95, 1.0, v94
	v_mov_b32_e32 v92, 0
	v_mov_b32_e32 v123, 0xff800000
	v_cndmask_b32_e32 v94, v94, v123, vcc
	v_cmp_lt_u32_e32 vcc, 0xfe, v120
	v_mov_b32_e32 v123, 0x7f800000
	v_subrev_u32_e32 v122, 0x100, v117
	v_cndmask_b32_e32 v95, v95, v123, vcc
	v_bfrev_b32_e32 v123, 1
	v_cmp_le_i32_e32 vcc, 240, v93
	s_cmp_eq_u64 vcc, -1
	s_cbranch_scc1 .Lp2_interior
	v_mul_f32_e32 v202, v106, v106
	v_fmac_f32_e32 v202, v107, v107
	v_fmac_f32_e32 v202, v108, v108
	v_fmac_f32_e32 v202, v109, v109
	v_fmac_f32_e32 v202, v110, v110
	v_fmac_f32_e32 v202, v111, v111
	v_fmac_f32_e32 v202, v112, v112
	v_fmac_f32_e32 v202, v113, v113
	v_max_f32_e32 v202, 0x358637bd, v202
	v_rsq_f32_e32 v202, v202
	s_mov_b32 s60, 0x100001
	s_mov_b32 s61, 0x10000100
	v_mul_f32_e32 v202, 4.0, v202
	v_cvt_pkrtz_f16_f32 v202, v202, v202
	v_pk_mul_f16 v84, v193, v202
	v_pk_mul_f16 v85, v194, v202
	v_pk_mul_f16 v86, v195, v202
	v_pk_mul_f16 v87, v196, v202
	v_cndmask_b32_e64 v84, 0, v84, s[60:61]
	v_cndmask_b32_e64 v85, 0, v85, s[60:61]
	v_cndmask_b32_e64 v86, 0, v86, s[60:61]
	v_cndmask_b32_e64 v87, 0, v87, s[60:61]
	v_mov_b32_e32 v88, 0x43000000
	v_mov_b32_e32 v89, 0
	v_mov_b32_e32 v90, 0
	v_mov_b32_e32 v91, 0
	s_waitcnt lgkmcnt(2)
	v_mfma_f32_16x16x32_f16 v[48:51], v[0:3], v[32:35], 0
	v_mfma_f32_16x16x32_f16 v[52:55], v[8:11], v[32:35], 0
	v_mfma_f32_16x16x32_f16 v[48:51], v[4:7], v[36:39], v[48:51]
	v_mfma_f32_16x16x32_f16 v[52:55], v[12:15], v[36:39], v[52:55]
	s_nop 3
	ds_read_b128 v[32:35], v118 offset:4096
	ds_read_b128 v[36:39], v119 offset:4096
	s_waitcnt lgkmcnt(2)
	v_mfma_f32_16x16x32_f16 v[56:59], v[0:3], v[40:43], 0
	v_cvt_pkrtz_f16_f32 v75, v54, v55
	v_cvt_pkrtz_f16_f32 v74, v52, v53
	v_pk_max_f16 v75, v75, 0
	v_pk_max_f16 v74, v74, 0
	v_mfma_f32_16x16x32_f16 v[60:63], v[8:11], v[40:43], 0
	v_cvt_pkrtz_f16_f32 v73, v50, v51
	v_cvt_pkrtz_f16_f32 v72, v48, v49
	v_pk_max_f16 v73, v73, 0
	v_mfma_f32_16x16x32_f16 v[56:59], v[4:7], v[44:47], v[56:59]
	v_pk_max_f16 v72, v72, 0
	v_mfma_f32_16x16x32_f16 v[60:63], v[12:15], v[44:47], v[60:63]
	s_nop 3
	v_mfma_f32_16x16x32_f16 v[76:79], v[84:87], v[72:75], v[88:91]
	ds_read_b128 v[40:43], v118 offset:6144
	ds_read_b128 v[44:47], v119 offset:6144
	s_waitcnt lgkmcnt(2)
	v_mfma_f32_16x16x32_f16 v[64:67], v[0:3], v[32:35], 0
	v_cvt_pkrtz_f16_f32 v75, v62, v63
	v_cvt_pkrtz_f16_f32 v74, v60, v61
	v_pk_max_f16 v75, v75, 0
	v_pk_max_f16 v74, v74, 0
	v_mfma_f32_16x16x32_f16 v[68:71], v[8:11], v[32:35], 0
	v_cvt_pkrtz_f16_f32 v73, v58, v59
	v_cvt_pkrtz_f16_f32 v72, v56, v57
	v_cmp_le_i32_e32 vcc, 0, v93
	v_pk_max_f16 v73, v73, 0
	v_mfma_f32_16x16x32_f16 v[64:67], v[4:7], v[36:39], v[64:67]
	v_pk_max_f16 v72, v72, 0
	v_cmp_le_f32_e64 s[60:61], v95, v76
	v_cmp_le_f32_e64 s[62:63], v94, v76
	v_mfma_f32_16x16x32_f16 v[68:71], v[12:15], v[36:39], v[68:71]
	v_mfma_f32_16x16x32_f16 v[80:83], v[84:87], v[72:75], v[88:91]
	s_and_b64 s[62:63], s[62:63], vcc
	s_and_b64 vcc, vcc, s[60:61]
	v_addc_co_u32_e32 v92, vcc, v92, v92, vcc
	s_andn2_b64 s[62:63], s[62:63], s[60:61]
	s_cbranch_scc1 .Lp2d_slow0

; template <int PASS> ...
;     ...
;                 else {
;                     if (bin > b0) { const unsigned pos = atomicAdd(&myctl[fq * 4 + 2], 1u); ((unsigned short*)myhist)[fq * 256 + (pos & 255u)] = (unsigned short)key; }
.Lp2d_back15:
	v_cmp_ne_u32_e32 vcc, 0, v92
	s_and_b64 exec, exec, vcc
	s_cbranch_execz .Lp2d_wdone
	v_bcnt_u32_b32 v201, v92, 0
	ds_add_rtn_u32 v201, v115, v201 offset:8
	s_waitcnt lgkmcnt(0)
.Lp2d_wloop:
	v_ffbh_u32_e32 v200, v92
	v_and_b32_e32 v203, 0xff, v201
	v_lshrrev_b32_e32 v202, v200, v123
	v_lshl_add_u32 v200, v200, 4, v122
	v_lshl_add_u32 v203, v203, 1, v142
	v_xor_b32_e32 v92, v92, v202
	v_add_u32_e32 v201, 1, v201
	ds_write_b16 v203, v200
	v_cmp_ne_u32_e32 vcc, 0, v92
	s_and_b64 exec, exec, vcc
	s_cbranch_execnz .Lp2d_wloop

; template <int PASS> ...
;     ...
;         for (int e = 0; e < 8; ++e) { const int T = Tbase + hb * 8 + e;
;             f32x4 a0 = (f32x4){0.f, 0.f, 0.f, 0.f}, a1 = a0;
;             a0 = __builtin_amdgcn_mfma_f32_16x16x32_f16(aq[0][0], kf[e][0], a0, 0, 0, 0); a0 = __builtin_amdgcn_mfma_f32_16x16x32_f16(aq[0][1], kf[e][1], a0, 0, 0, 0);
;             a1 = __builtin_amdgcn_mfma_f32_16x16x32_f16(aq[1][0], kf[e][0], a1, 0, 0, 0); a1 = __builtin_amdgcn_mfma_f32_16x16x32_f16(aq[1][1], kf[e][1], a1, 0, 0, 0);
;             const h16x2 z2 = (h16x2){(h16)0.f, (h16)0.f};
;             const h16x2 r0 = __builtin_elementwise_max(__builtin_bit_cast(h16x2, __builtin_amdgcn_cvt_pkrtz(a0[0], a0[1])), z2), r1 = __builtin_elementwise_max(__builtin_bit_cast(h16x2, __builtin_amdgcn_cvt_pkrtz(a0[2], a0[3])), z2);
;             const h16x2 r2 = __builtin_elementwise_max(__builtin_bit_cast(h16x2, __builtin_amdgcn_cvt_pkrtz(a1[0], a1[1])), z2), r3 = __builtin_elementwise_max(__builtin_bit_cast(h16x2, __builtin_amdgcn_cvt_pkrtz(a1[2], a1[3])), z2);
;             const float sa = __builtin_amdgcn_fdot2(r0, wp[0], __builtin_amdgcn_fdot2(r1, wp[1], __builtin_amdgcn_fdot2(r2, wp[2], __builtin_amdgcn_fdot2(r3, wp[3], 0.f, false), false), false), false);
;             const int key = 16 * T + fr;
;             if (key <= tq) {
;                 const unsigned bin = (unsigned)(int)fminf(fmaxf(sa * 32.f + 128.f, 0.f), 255.f);
;                 if (PASS == 1) { if (bin >= b0) atomicAdd(&myhist[fq * 256 + bin], 1u); }
;                 else {
;                     if (bin > b0) { const unsigned pos = atomicAdd(&myctl[fq * 4 + 2], 1u); ((unsigned short*)myhist)[fq * 256 + (pos & 255u)] = (unsigned short)key; }
;                     else if (bin == b0) { const unsigned c = atomicAdd(&myctl[fq * 4 + 3], 1u);
; __device__ __forceinline__ void dsa_select(const h16* PROJ, unsigned short* IDX, int* CNT, unsigned char* shm, unsigned* bar, unsigned xcc, unsigned xrank) {
;     ...
;             float wv[8];
;             { const h16x8 w8 = *(const h16x8*)(PROJ + O_WI + (size_t)(tokbase + tq) * 8);
; #pragma unroll
;               for (int h = 0; h < 8; ++h) wv[h] = (float)w8[h] * 0.04419417382415922f; }
;             h16x2 wp[4];
; #pragma unroll
;             for (int h = 0; h < 4; ++h) { wp[h].x = (h16)wv[(h >> 1) * 4 + (h & 1) * 2]; wp[h].y = (h16)wv[(h >> 1) * 4 + (h & 1) * 2 + 1]; }
.Lp2_interior:
	v_mul_f32_e32 v202, v106, v106
	v_fmac_f32_e32 v202, v107, v107
	v_fmac_f32_e32 v202, v108, v108
	v_fmac_f32_e32 v202, v109, v109
	v_fmac_f32_e32 v202, v110, v110
	v_fmac_f32_e32 v202, v111, v111
	v_fmac_f32_e32 v202, v112, v112
	v_fmac_f32_e32 v202, v113, v113
	v_max_f32_e32 v202, 0x358637bd, v202
	v_rsq_f32_e32 v202, v202
	s_mov_b32 s60, 0x100001
	s_mov_b32 s61, 0x10000100
	v_mul_f32_e32 v202, 4.0, v202
	v_cvt_pkrtz_f16_f32 v202, v202, v202
	v_pk_mul_f16 v84, v193, v202
	v_pk_mul_f16 v85, v194, v202
	v_pk_mul_f16 v86, v195, v202
	v_pk_mul_f16 v87, v196, v202
	v_cndmask_b32_e64 v84, 0, v84, s[60:61]
	v_cndmask_b32_e64 v85, 0, v85, s[60:61]
	v_cndmask_b32_e64 v86, 0, v86, s[60:61]
	v_cndmask_b32_e64 v87, 0, v87, s[60:61]
	v_mov_b32_e32 v88, 0x43000000
	v_mov_b32_e32 v89, 0
	v_mov_b32_e32 v90, 0
	v_mov_b32_e32 v91, 0
	s_waitcnt lgkmcnt(2)
	v_mfma_f32_16x16x32_f16 v[48:51], v[0:3], v[32:35], 0
	v_mfma_f32_16x16x32_f16 v[52:55], v[8:11], v[32:35], 0
	v_mfma_f32_16x16x32_f16 v[48:51], v[4:7], v[36:39], v[48:51]
	v_mfma_f32_16x16x32_f16 v[52:55], v[12:15], v[36:39], v[52:55]
	s_nop 3
	ds_read_b128 v[32:35], v118 offset:4096
	ds_read_b128 v[36:39], v119 offset:4096
	s_waitcnt lgkmcnt(2)
	v_mfma_f32_16x16x32_f16 v[56:59], v[0:3], v[40:43], 0
	v_cvt_pkrtz_f16_f32 v75, v54, v55
	v_cvt_pkrtz_f16_f32 v74, v52, v53
	v_pk_max_f16 v75, v75, 0
	v_pk_max_f16 v74, v74, 0
	v_mfma_f32_16x16x32_f16 v[60:63], v[8:11], v[40:43], 0
	v_cvt_pkrtz_f16_f32 v73, v50, v51
	v_cvt_pkrtz_f16_f32 v72, v48, v49
	v_pk_max_f16 v73, v73, 0
	v_mfma_f32_16x16x32_f16 v[56:59], v[4:7], v[44:47], v[56:59]
	v_pk_max_f16 v72, v72, 0
	v_mfma_f32_16x16x32_f16 v[60:63], v[12:15], v[44:47], v[60:63]
	s_nop 3
	s_nop 1
	v_mfma_f32_16x16x32_f16 v[76:79], v[84:87], v[72:75], v[88:91]
	ds_read_b128 v[40:43], v118 offset:6144
	ds_read_b128 v[44:47], v119 offset:6144
	s_waitcnt lgkmcnt(2)
	v_mfma_f32_16x16x32_f16 v[64:67], v[0:3], v[32:35], 0
	v_cvt_pkrtz_f16_f32 v75, v62, v63
	v_cvt_pkrtz_f16_f32 v74, v60, v61
	v_pk_max_f16 v75, v75, 0
	v_pk_max_f16 v74, v74, 0
	v_mfma_f32_16x16x32_f16 v[68:71], v[8:11], v[32:35], 0
	v_cvt_pkrtz_f16_f32 v73, v58, v59
	v_cvt_pkrtz_f16_f32 v72, v56, v57
	v_pk_max_f16 v73, v73, 0
	v_mfma_f32_16x16x32_f16 v[64:67], v[4:7], v[36:39], v[64:67]
	v_pk_max_f16 v72, v72, 0
	v_cmp_le_f32_e64 s[62:63], v94, v76
	v_cmp_le_f32_e32 vcc, v95, v76
	v_mfma_f32_16x16x32_f16 v[68:71], v[12:15], v[36:39], v[68:71]
	s_nop 1
	v_mfma_f32_16x16x32_f16 v[80:83], v[84:87], v[72:75], v[88:91]
	s_andn2_b64 s[62:63], s[62:63], vcc
	v_addc_co_u32_e32 v92, vcc, v92, v92, vcc
	s_cmp_lg_u64 s[62:63], 0
	s_cbranch_scc1 .Lp2i_slow0
